# attention item start: first chunk's K loads issued right after the Q fragments reach LDS, ahead of the window-mask set-up
# speedup vs baseline: 1.0142x; 1.0072x over previous
.LBB0_347:
	v_and_b32_e32 v160, -4, v32
	v_sub_u32_e64 v32, v161, 8 clamp
	v_sub_u32_e32 v32, v160, v32
	v_add_u32_e32 v44, 33, v32
	v_add_u32_e32 v37, 1, v32
	v_add_u32_e32 v45, 34, v32
	v_cmp_gt_u32_e32 vcc, 16, v44
	v_sub_u32_e32 v35, v160, v161
	v_add_u32_e32 v38, 2, v32
	v_add_u32_e32 v46, 35, v32
	v_cmp_gt_u32_e64 s[46:47], 16, v37
	v_cndmask_b32_e32 v37, 0, v231, vcc
	v_cmp_gt_u32_e32 vcc, 16, v45
	v_add_u32_e32 v39, 3, v32
	v_and_b32_e32 v43, -16, v32
	v_add_u32_e32 v49, -8, v35
	v_cmp_gt_u32_e64 s[48:49], 16, v38
	v_cndmask_b32_e32 v38, 0, v232, vcc
	v_cmp_gt_u32_e32 vcc, 16, v46
	s_movk_i32 s30, 0xffd0
	v_add_u32_e32 v40, 17, v32
	v_add_u32_e32 v47, 49, v32
	v_cmp_gt_u32_e64 s[50:51], 16, v39
	v_cndmask_b32_e32 v39, 0, v233, vcc
	v_cmp_eq_u32_e32 vcc, s30, v43
	v_and_b32_e32 v46, -16, v49
	s_movk_i32 s26, 0xffe0
	v_lshl_add_u32 v168, v34, 4, s55
	s_movk_i32 s27, 0xffef
	v_add_u32_e32 v41, 18, v32
	v_add_u32_e32 v48, 50, v32
	v_cmp_gt_u32_e64 s[52:53], 16, v40
	v_cndmask_b32_e32 v40, 0, v234, vcc
	v_cmp_gt_u32_e32 vcc, 16, v47
	v_cmp_eq_u32_e64 s[58:59], s26, v46
	v_cmp_gt_u32_e64 s[42:43], 16, v32
	v_cmp_lt_u32_e64 s[44:45], s27, v32
	v_add_u32_e32 v42, 19, v32
	v_add_u32_e32 v32, 51, v32
	v_cmp_gt_u32_e64 s[54:55], 16, v41
	v_cndmask_b32_e32 v41, 0, v235, vcc
	v_cmp_gt_u32_e32 vcc, 16, v48
	v_add_u32_e32 v50, 43, v35
	v_cmp_gt_u32_e64 s[56:57], 16, v42
	v_cndmask_b32_e32 v42, 0, v236, vcc
	v_cmp_gt_u32_e32 vcc, 16, v32
	v_add_u32_e32 v51, 42, v35
	v_add_u32_e32 v52, 41, v35
	v_cndmask_b32_e32 v32, 0, v237, vcc
	v_cmp_gt_u32_e32 vcc, 16, v50
	v_add_u32_e32 v53, 27, v35
	v_readlane_b32 s31, v252, 41
	v_cndmask_b32_e32 v43, 0, v237, vcc
	v_cmp_gt_u32_e32 vcc, 16, v51
	v_mov_b32_e32 v169, 0xf149f2ca
	v_mov_b32_e32 v171, 0xf149f2ca
	v_cndmask_b32_e32 v44, 0, v236, vcc
	v_cmp_gt_u32_e32 vcc, 16, v52
	v_mov_b32_e32 v172, 0xf149f2ca
	v_mov_b32_e32 v170, 0xf149f2ca
	v_cndmask_b32_e32 v45, 0, v235, vcc
	v_cmp_eq_u32_e32 vcc, s30, v46
	v_readlane_b32 s60, v252, 47
	s_waitcnt vmcnt(7)
	ds_write_b128 v168, v[0:3] offset:20480
	s_waitcnt vmcnt(6)
	ds_write_b128 v168, v[4:7] offset:21504
	s_waitcnt vmcnt(5)
	ds_write_b128 v168, v[8:11] offset:22528
	s_waitcnt vmcnt(4)
	ds_write_b128 v168, v[12:15] offset:23552
	s_waitcnt vmcnt(3)
	ds_write_b128 v168, v[16:19] offset:24576
	s_waitcnt vmcnt(2)
	ds_write_b128 v168, v[20:23] offset:25600
	s_waitcnt vmcnt(1)
	ds_write_b128 v168, v[24:27] offset:26624
	s_waitcnt vmcnt(0)
	ds_write_b128 v168, v[28:31] offset:27648
	v_readlane_b32 s98, v252, 38
	v_readlane_b32 s99, v252, 39
	s_nop 3
	s_add_u32 s98, s98, s24
	s_addc_u32 s99, s99, s25
	v_lshl_add_u64 v[120:121], s[98:99], 0, v[162:163]
	s_add_u32 s98, s98, 0x4000
	s_addc_u32 s99, s99, 0
	v_lshl_add_u64 v[122:123], s[98:99], 0, v[162:163]
	global_load_dwordx4 v[24:27], v[120:121], off
	global_load_dwordx4 v[16:19], v[120:121], off offset:1024
	global_load_dwordx4 v[28:31], v[122:123], off
	global_load_dwordx4 v[20:23], v[122:123], off offset:1024
	v_cndmask_b32_e64 v3, 0, v238, s[58:59]
	v_cmp_lt_u32_e64 s[58:59], s27, v49
	v_add_u32_e32 v9, -6, v35
	v_add_u32_e32 v10, -7, v35
	v_cndmask_b32_e64 v7, 0, 16, s[58:59]
	v_cmp_gt_u32_e64 s[58:59], 16, v49
	v_add_u32_e32 v6, 9, v35
	v_add_u32_e32 v8, -5, v35
	v_cmp_gt_u32_e64 s[74:75], 16, v9
	v_cmp_gt_u32_e64 s[76:77], 16, v10
	v_cndmask_b32_e64 v11, 0, 1, s[58:59]
	v_add_u32_e32 v4, 11, v35
	v_add_u32_e32 v5, 10, v35
	v_cmp_gt_u32_e64 s[70:71], 16, v6
	v_cmp_gt_u32_e64 s[72:73], 16, v8
	v_cndmask_b32_e64 v9, 0, 4, s[74:75]
	v_cndmask_b32_e64 v10, 0, 2, s[76:77]
	v_or_b32_e32 v7, v7, v11
	v_add_u32_e32 v1, 26, v35
	v_add_u32_e32 v2, 25, v35
	v_cmp_gt_u32_e64 s[66:67], 16, v4
	v_cmp_gt_u32_e64 s[68:69], 16, v5
	v_cndmask_b32_e64 v6, 0, 32, s[70:71]
	v_cndmask_b32_e64 v8, 0, 8, s[72:73]
	v_or3_b32 v7, v7, v10, v9
	v_cmp_gt_u32_e64 s[62:63], 16, v1
	v_cmp_gt_u32_e64 s[64:65], 16, v2
	v_cndmask_b32_e64 v4, 0, v239, s[66:67]
	v_cndmask_b32_e64 v5, 0, 64, s[68:69]
	v_or3_b32 v6, v7, v8, v6
	v_cndmask_b32_e32 v47, 0, v234, vcc
	v_cmp_gt_u32_e32 vcc, 16, v53
	v_cndmask_b32_e64 v1, 0, v232, s[62:63]
	v_cndmask_b32_e64 v2, 0, v231, s[64:65]
	v_or3_b32 v4, v6, v5, v4
	v_cndmask_b32_e32 v0, 0, v233, vcc
	v_or3_b32 v1, v4, v2, v1
	v_or3_b32 v0, v1, v0, v45
	v_or3_b32 v1, v41, v42, v40
	v_or3_b32 v0, v0, v44, v43
	v_or3_b32 v1, v1, v39, v38
	v_or3_b32 v0, v0, v3, v47
	v_or3_b32 v1, v1, v37, v32
	v_lshl_add_u32 v32, v0, 16, v1
	v_subrev_u32_e32 v1, 23, v35
	v_cmp_gt_u32_e64 s[78:79], 16, v1
	v_subrev_u32_e32 v1, 22, v35
	v_subrev_u32_e32 v0, 24, v35
	v_cndmask_b32_e64 v37, 0, 2, s[78:79]
	v_cmp_gt_u32_e64 s[78:79], 16, v1
	v_subrev_u32_e32 v1, 21, v35
	v_cmp_gt_u32_e64 s[58:59], 16, v0
	v_cndmask_b32_e64 v38, 0, 4, s[78:79]
	v_cmp_gt_u32_e64 s[78:79], 16, v1
	v_cndmask_b32_e64 v42, 0, v239, s[72:73]
	v_cndmask_b32_e64 v40, 0, 32, s[76:77]
	v_cndmask_b32_e64 v35, 0, 8, s[78:79]
	v_cmp_lt_u32_e64 s[78:79], s27, v0
	v_and_b32_e32 v0, -16, v0
	v_cmp_eq_u32_e64 s[72:73], s26, v0
	v_cndmask_b32_e64 v41, 0, 64, s[74:75]
	v_cndmask_b32_e64 v39, 0, 16, s[78:79]
	v_cndmask_b32_e64 v43, 0, v238, s[72:73]
	v_or_b32_e32 v1, v42, v43
	v_or3_b32 v1, v1, v40, v41
	v_or3_b32 v1, v1, v39, v38
	v_or3_b32 v1, v1, v37, v35
	v_cndmask_b32_e64 v2, 0, v231, s[70:71]
	v_cndmask_b32_e64 v3, 0, v232, s[68:69]
	v_or3_b32 v44, v2, v3, v1
	v_cndmask_b32_e64 v1, 0, v233, s[66:67]
	v_cmp_eq_u32_e64 s[66:67], s30, v0
	v_bfrev_b32_e32 v7, 8
	s_waitcnt lgkmcnt(0)
	s_movk_i32 s72, 0x4000
	v_cndmask_b32_e64 v0, 0, v234, s[66:67]
	v_or3_b32 v45, v0, v1, v44
	v_cndmask_b32_e64 v0, 0, v235, s[64:65]
	v_cndmask_b32_e64 v1, 0, v236, s[62:63]
	v_or3_b32 v46, v0, v1, v45
	v_min_u32_e32 v1, 8, v161
	v_sub_u32_e32 v1, v160, v1
	v_add_u32_e32 v3, 11, v1
	v_cndmask_b32_e32 v0, 0, v237, vcc
	v_cmp_gt_u32_e32 vcc, 16, v3
	v_bfrev_b32_e32 v3, 1
	v_add_u32_e32 v4, 10, v1
	v_subrev_u32_e32 v2, 40, v1
	v_cndmask_b32_e32 v3, 0, v3, vcc
	v_cmp_gt_u32_e32 vcc, 16, v4
	v_add_u32_e32 v5, 9, v1
	v_and_b32_e32 v6, -16, v2
	v_cndmask_b32_e64 v4, 0, 2.0, vcc
	v_cmp_gt_u32_e32 vcc, 16, v5
	v_bfrev_b32_e32 v5, 4
	v_add_u32_e32 v8, -5, v1
	v_cndmask_b32_e32 v5, 0, v5, vcc
	v_cmp_eq_u32_e32 vcc, s30, v6
	v_add_u32_e32 v9, -6, v1
	v_add_u32_e32 v10, -7, v1
	v_cndmask_b32_e32 v7, 0, v7, vcc
	v_cmp_gt_u32_e32 vcc, 16, v8
	v_bfrev_b32_e32 v8, 16
	v_subrev_u32_e32 v11, 21, v1
	v_cndmask_b32_e32 v8, 0, v8, vcc
	v_cmp_gt_u32_e32 vcc, 16, v9
	v_bfrev_b32_e32 v9, 32
	v_subrev_u32_e32 v12, 22, v1
	v_cndmask_b32_e32 v9, 0, v9, vcc
	v_cmp_gt_u32_e32 vcc, 16, v10
	v_bfrev_b32_e32 v10, 64
	v_subrev_u32_e32 v13, 23, v1
	v_cndmask_b32_e32 v10, 0, v10, vcc
	v_cmp_eq_u32_e32 vcc, s26, v6
	v_subrev_u32_e32 v14, 37, v1
	v_subrev_u32_e32 v15, 38, v1
	v_cndmask_b32_e32 v6, 0, v245, vcc
	v_cmp_gt_u32_e32 vcc, 16, v11
	v_mov_b32_e32 v11, 0x800000
	v_subrev_u32_e32 v1, 39, v1
	v_cndmask_b32_e32 v11, 0, v11, vcc
	v_cmp_gt_u32_e32 vcc, 16, v12
	v_mov_b32_e32 v12, 0x400000
	v_readlane_b32 s26, v252, 38
	v_cndmask_b32_e32 v12, 0, v12, vcc
	v_cmp_gt_u32_e32 vcc, 16, v13
	v_mov_b32_e32 v13, 0x200000
	s_add_u32 s26, s26, s24
	v_cndmask_b32_e32 v13, 0, v13, vcc
	v_cmp_lt_u32_e32 vcc, s27, v2
	v_readlane_b32 s27, v252, 39
	s_addc_u32 s27, s27, s25
	v_cndmask_b32_e32 v2, 0, v250, vcc
	v_cmp_gt_u32_e32 vcc, 16, v14
	v_readlane_b32 s30, v252, 40
	v_bfe_i32 v156, v32, 16, 1
	v_cndmask_b32_e32 v14, 0, v251, vcc
	v_cmp_gt_u32_e32 vcc, 16, v15
	v_bfe_i32 v157, v32, 17, 1
	v_bfe_i32 v158, v32, 18, 1
	v_cndmask_b32_e32 v15, 0, v240, vcc
	v_cmp_gt_u32_e32 vcc, 16, v1
	v_bfe_i32 v159, v32, 19, 1
	v_bfe_i32 v173, v32, 20, 1
	v_cndmask_b32_e32 v1, 0, v241, vcc
	v_or3_b32 v1, v2, v1, v15
	v_or3_b32 v1, v1, v14, v13
	v_or3_b32 v1, v1, v12, v11
	v_or3_b32 v1, v1, v10, v9
	v_or3_b32 v1, v1, v8, v5
	v_or3_b32 v1, v1, v4, v3
	v_or3_b32 v0, v1, v0, v6
	v_or3_b32 v47, v0, v7, v46
	v_lshl_add_u64 v[0:1], s[26:27], 0, v[162:163]
	s_mov_b32 s26, s34
	v_writelane_b32 v254, s26, 58
	v_writelane_b32 v254, s27, 59
	s_lshl_b64 s[26:27], s[34:35], 12
	s_add_u32 s30, s30, s26
	s_addc_u32 s31, s31, s27
	v_add_co_u32_e32 v0, vcc, s72, v0
	v_lshl_add_u64 v[12:13], s[30:31], 0, v[162:163]
	s_nop 0
	v_addc_co_u32_e32 v1, vcc, 0, v1, vcc
	s_nop 0
	global_load_dwordx4 v[0:3], v[12:13], off
	global_load_dwordx4 v[4:7], v[12:13], off offset:1024
	global_load_dwordx4 v[8:11], v[12:13], off offset:2048
	s_nop 0
	global_load_dwordx4 v[12:15], v[12:13], off offset:3072
	v_readlane_b32 s30, v252, 48
	s_add_u32 s30, s30, s24
	v_readlane_b32 s31, v252, 50
	s_addc_u32 s31, s31, s25
	v_bfe_i32 v174, v32, 21, 1
	v_bfe_i32 v175, v32, 22, 1
	v_bfe_i32 v176, v32, 23, 1
	v_bfe_i32 v188, v32, 24, 1
	v_bfe_i32 v189, v32, 25, 1
	v_bfe_i32 v190, v32, 26, 1
	v_bfe_i32 v191, v32, 27, 1
	v_bfe_i32 v192, v32, 28, 1
	v_bfe_i32 v193, v32, 29, 1
	v_bfe_i32 v194, v32, 30, 1
	v_ashrrev_i32_e32 v195, 31, v32
	v_and_b32_e32 v32, -16, v34
	v_lshl_add_u64 v[164:165], s[30:31], 0, v[162:163]
	v_readlane_b32 s30, v252, 52
	v_add_u32_e32 v32, s0, v32
	v_lshlrev_b32_e32 v34, 2, v161
	s_add_u32 s30, s30, s26
	v_readlane_b32 s31, v252, 54
	v_sub_u32_e32 v32, v32, v34
	v_readlane_b32 s0, v254, 14
	s_addc_u32 s31, s31, s27
	v_lshl_add_u64 v[166:167], s[30:31], 0, v[162:163]
	v_add_u32_e32 v212, s0, v32
	v_readlane_b32 s0, v254, 16
	s_add_u32 s30, s0, s24
	v_readlane_b32 s0, v254, 18
	s_addc_u32 s31, s0, s25
	v_readlane_b32 s0, v254, 17
	v_bfe_i32 v183, v35, 3, 1
	v_lshl_add_u64 v[152:153], s[30:31], 0, v[162:163]
	s_add_u32 s30, s0, s26
	v_readlane_b32 s0, v254, 19
	v_mov_b32_e32 v34, v33
	v_mov_b32_e32 v35, v33
	v_bfe_i32 v185, v40, 5, 1
	v_bfe_i32 v186, v41, 6, 1
	v_bfe_i32 v187, v42, 7, 1
	v_bfe_i32 v196, v43, 8, 1
	v_bfe_i32 v197, v44, 9, 1
	v_bfe_i32 v198, v44, 10, 1
	v_bfe_i32 v199, v45, 11, 1
	v_bfe_i32 v200, v45, 12, 1
	v_bfe_i32 v201, v46, 13, 1
	v_bfe_i32 v202, v46, 14, 1
	v_bfe_i32 v203, v47, 15, 1
	v_bfe_i32 v204, v47, 24, 1
	v_bfe_i32 v205, v47, 25, 1
	v_bfe_i32 v206, v47, 26, 1
	v_bfe_i32 v207, v47, 27, 1
	v_bfe_i32 v208, v47, 28, 1
	v_bfe_i32 v209, v47, 29, 1
	v_bfe_i32 v210, v47, 30, 1
	v_ashrrev_i32_e32 v211, 31, v47
	s_addc_u32 s31, s0, s27
	v_mov_b32_e32 v32, v33
	v_mov_b64_e32 v[58:59], v[34:35]
	v_mov_b64_e32 v[42:43], v[34:35]
	v_mov_b64_e32 v[46:47], v[34:35]
	v_mov_b64_e32 v[50:51], v[34:35]
	v_mov_b64_e32 v[54:55], v[34:35]
	v_mov_b64_e32 v[98:99], v[34:35]
	v_mov_b64_e32 v[82:83], v[34:35]
	v_mov_b64_e32 v[86:87], v[34:35]
	v_mov_b64_e32 v[90:91], v[34:35]
	v_mov_b64_e32 v[94:95], v[34:35]
	v_mov_b64_e32 v[118:119], v[34:35]
	v_mov_b64_e32 v[102:103], v[34:35]
	v_mov_b64_e32 v[106:107], v[34:35]
	v_mov_b64_e32 v[110:111], v[34:35]
	v_mov_b64_e32 v[114:115], v[34:35]
	v_mov_b64_e32 v[78:79], v[34:35]
	v_mov_b64_e32 v[62:63], v[34:35]
	v_mov_b64_e32 v[66:67], v[34:35]
	v_mov_b64_e32 v[70:71], v[34:35]
	v_mov_b64_e32 v[74:75], v[34:35]
	v_bfe_i32 v177, v37, 1, 1
	v_bfe_i32 v178, v38, 2, 1
	v_bfe_i32 v184, v39, 4, 1
	v_lshl_add_u64 v[154:155], s[30:31], 0, v[162:163]
	s_mov_b64 s[34:35], 0
	v_readlane_b32 s30, v254, 13
	v_mov_b64_e32 v[56:57], v[32:33]
	v_mov_b64_e32 v[40:41], v[32:33]
	v_mov_b64_e32 v[44:45], v[32:33]
	v_mov_b64_e32 v[48:49], v[32:33]
	v_mov_b64_e32 v[52:53], v[32:33]
	v_mov_b64_e32 v[96:97], v[32:33]
	v_mov_b64_e32 v[80:81], v[32:33]
	v_mov_b64_e32 v[84:85], v[32:33]
	v_mov_b64_e32 v[88:89], v[32:33]
	v_mov_b64_e32 v[92:93], v[32:33]
	v_mov_b64_e32 v[116:117], v[32:33]
	v_mov_b64_e32 v[100:101], v[32:33]
	v_mov_b64_e32 v[104:105], v[32:33]
	v_mov_b64_e32 v[108:109], v[32:33]
	v_mov_b64_e32 v[112:113], v[32:33]
	v_mov_b64_e32 v[76:77], v[32:33]
	v_mov_b64_e32 v[60:61], v[32:33]
	v_mov_b64_e32 v[64:65], v[32:33]
	v_mov_b64_e32 v[68:69], v[32:33]
	v_mov_b64_e32 v[72:73], v[32:33]
	s_branch .LBB0_349
